# v1 + s_setprio ladder inside the tile (3,2,1,0 by quarter) so the SIMD partner that is behind outranks the one ahead
# speedup vs baseline: 1.0232x; 1.0028x over previous
.LBB0_531:
	s_add_i32 s10, s33, 2
	s_cmp_ge_u32 s10, s28
	s_cselect_b64 s[22:23], -1, 0
	s_mov_b64 s[34:35], -1
	s_cmp_gt_i32 s33, s21
	s_cbranch_scc1 .Lat1_skip
	s_and_b64 vcc, exec, s[22:23]
	s_cbranch_vccnz .Lat1_nodma
	s_setprio 3
	v_mov_b32_e32 v206, v217
	s_mul_i32 s10, s0, 0xa000
	v_lshlrev_b32_e32 v209, 3, v206
	v_lshrrev_b32_e32 v207, 1, v206
	v_lshlrev_b32_e32 v208, 7, v206
	v_and_b32_e32 v209, 8, v209
	v_ashrrev_i32_e32 v206, 5, v206
	v_add_u32_e32 v206, v209, v206
	v_and_b32_e32 v208, 0xf00, v208
	v_bitop3_b32 v209, v206, v207, 7 bitop3:0x78
	v_add_u32_e32 v210, 2, v206
	v_add_u32_e32 v211, 4, v206
	v_add_u32_e32 v206, 6, v206
	v_add_u32_e32 v208, s10, v208
	v_bitop3_b32 v210, v210, v207, 7 bitop3:0x78
	v_bitop3_b32 v211, v211, v207, 7 bitop3:0x78
	v_bitop3_b32 v206, v206, v207, 7 bitop3:0x78
	v_lshl_add_u32 v14, v209, 4, v208
	v_lshl_add_u32 v15, v210, 4, v208
	v_lshl_add_u32 v176, v211, 4, v208
	v_lshl_add_u32 v177, v206, 4, v208
	ds_read_b128 v[144:147], v14 offset:0
	ds_read_b128 v[148:151], v15 offset:0
	ds_read_b128 v[152:155], v176 offset:0
	ds_read_b128 v[156:159], v177 offset:0
	ds_read_b128 v[160:163], v14 offset:8192
	ds_read_b128 v[164:167], v15 offset:8192
	ds_read_b128 v[168:171], v176 offset:8192
	ds_read_b128 v[172:175], v177 offset:8192
	ds_read_b128 v[2:5], v14 offset:16384
	ds_read_b128 v[6:9], v15 offset:16384
	ds_read_b128 v[10:13], v176 offset:16384
	ds_read_b128 v[238:241], v177 offset:16384
	v_mad_u64_u32 v[202:203], s[10:11], s86, v228, v[180:181]
	s_mul_i32 s10, s7, 0xa000
	s_add_i32 s10, s9, s10
	s_mov_b32 m0, s10
	v_lshl_add_u64 v[204:205], v[202:203], 0, s[94:95]
	global_load_lds_dwordx4 v[202:203], off
	s_add_i32 m0, s10, 0x2000
	v_lshl_add_u64 v[202:203], v[202:203], 0, s[96:97]
	global_load_lds_dwordx4 v[204:205], off
	s_waitcnt lgkmcnt(8)
	v_mfma_f32_32x32x16_bf16 v[80:95], v[144:147], v[132:135], 0
	s_add_i32 m0, s10, 0x4000
	v_mfma_f32_32x32x16_bf16 v[80:95], v[148:151], v[128:131], v[80:95]
	global_load_lds_dwordx4 v[202:203], off
	v_lshl_add_u64 v[202:203], s[86:87], 1, v[182:183]
	s_add_i32 m0, s10, 0x6000
	v_mfma_f32_32x32x16_bf16 v[80:95], v[152:155], v[124:127], v[80:95]
	global_load_lds_dwordx4 v[202:203], off
	v_lshl_add_u64 v[202:203], v[202:203], 0, s[92:93]
	s_add_i32 m0, s10, 0x8000
	v_mfma_f32_32x32x16_bf16 v[80:95], v[156:159], v[120:123], v[80:95]
	global_load_lds_dwordx4 v[202:203], off
	ds_read_b128 v[144:147], v14 offset:4096
	ds_read_b128 v[148:151], v15 offset:4096
	ds_read_b128 v[152:155], v176 offset:4096
	ds_read_b128 v[156:159], v177 offset:4096
	s_waitcnt lgkmcnt(8)
	v_mfma_f32_32x32x16_bf16 v[80:95], v[160:163], v[116:119], v[80:95]
	v_mfma_f32_32x32x16_bf16 v[80:95], v[164:167], v[112:115], v[80:95]
	v_mfma_f32_32x32x16_bf16 v[80:95], v[168:171], v[108:111], v[80:95]
	v_mfma_f32_32x32x16_bf16 v[80:95], v[172:175], v[104:107], v[80:95]
	ds_read_b128 v[160:163], v14 offset:12288
	ds_read_b128 v[164:167], v15 offset:12288
	ds_read_b128 v[168:171], v176 offset:12288
	ds_read_b128 v[172:175], v177 offset:12288
	s_waitcnt lgkmcnt(8)
	v_mfma_f32_32x32x16_bf16 v[80:95], v[2:5], v[100:103], v[80:95]
	v_mfma_f32_32x32x16_bf16 v[80:95], v[6:9], v[140:143], v[80:95]
	v_mfma_f32_32x32x16_bf16 v[80:95], v[10:13], v[96:99], v[80:95]
	v_mfma_f32_32x32x16_bf16 v[80:95], v[238:241], v[136:139], v[80:95]
	s_setprio 2
	ds_read_b128 v[2:5], v14 offset:20480
	ds_read_b128 v[6:9], v15 offset:20480
	ds_read_b128 v[10:13], v176 offset:20480
	ds_read_b128 v[238:241], v177 offset:20480
	s_waitcnt lgkmcnt(8)
	v_mfma_f32_32x32x16_bf16 v[184:199], v[144:147], v[132:135], 0
	v_mfma_f32_32x32x16_bf16 v[184:199], v[148:151], v[128:131], v[184:199]
	v_mfma_f32_32x32x16_bf16 v[184:199], v[152:155], v[124:127], v[184:199]
	v_mfma_f32_32x32x16_bf16 v[184:199], v[156:159], v[120:123], v[184:199]
	ds_read_b128 v[144:147], v14 offset:24576
	ds_read_b128 v[148:151], v14 offset:28672
	ds_read_b128 v[152:155], v14 offset:32768
	ds_read_b128 v[156:159], v14 offset:36864
	s_waitcnt lgkmcnt(8)
	v_mfma_f32_32x32x16_bf16 v[184:199], v[160:163], v[116:119], v[184:199]
	v_med3_f32 v80, v80, s4, v236
	v_exp_f32_e32 v80, v80
	v_med3_f32 v81, v81, s4, v236
	v_exp_f32_e32 v81, v81
	v_mfma_f32_32x32x16_bf16 v[184:199], v[164:167], v[112:115], v[184:199]
	v_med3_f32 v82, v82, s4, v236
	v_exp_f32_e32 v82, v82
	v_med3_f32 v83, v83, s4, v236
	v_exp_f32_e32 v83, v83
	v_mfma_f32_32x32x16_bf16 v[184:199], v[168:171], v[108:111], v[184:199]
	v_med3_f32 v84, v84, s4, v236
	v_exp_f32_e32 v84, v84
	v_med3_f32 v85, v85, s4, v236
	v_exp_f32_e32 v85, v85
	v_mfma_f32_32x32x16_bf16 v[184:199], v[172:175], v[104:107], v[184:199]
	v_med3_f32 v86, v86, s4, v236
	v_exp_f32_e32 v86, v86
	v_med3_f32 v87, v87, s4, v236
	v_exp_f32_e32 v87, v87
	ds_read_b128 v[160:163], v15 offset:24576
	ds_read_b128 v[164:167], v15 offset:28672
	ds_read_b128 v[168:171], v15 offset:32768
	ds_read_b128 v[172:175], v15 offset:36864
	s_waitcnt lgkmcnt(8)
	v_mfma_f32_32x32x16_bf16 v[184:199], v[2:5], v[100:103], v[184:199]
	v_med3_f32 v88, v88, s4, v236
	v_exp_f32_e32 v88, v88
	v_med3_f32 v89, v89, s4, v236
	v_exp_f32_e32 v89, v89
	v_add_f32_e32 v200, v80, v81
	v_add_f32_e32 v200, v200, v82
	v_mfma_f32_32x32x16_bf16 v[184:199], v[6:9], v[140:143], v[184:199]
	v_med3_f32 v90, v90, s4, v236
	v_exp_f32_e32 v90, v90
	v_med3_f32 v91, v91, s4, v236
	v_exp_f32_e32 v91, v91
	v_add_f32_e32 v200, v200, v83
	v_add_f32_e32 v200, v200, v84
	v_mfma_f32_32x32x16_bf16 v[184:199], v[10:13], v[96:99], v[184:199]
	v_med3_f32 v92, v92, s4, v236
	v_exp_f32_e32 v92, v92
	v_med3_f32 v93, v93, s4, v236
	v_exp_f32_e32 v93, v93
	v_add_f32_e32 v200, v200, v85
	v_add_f32_e32 v200, v200, v86
	v_mfma_f32_32x32x16_bf16 v[184:199], v[238:241], v[136:139], v[184:199]
	v_med3_f32 v94, v94, s4, v236
	v_exp_f32_e32 v94, v94
	v_med3_f32 v95, v95, s4, v236
	v_exp_f32_e32 v95, v95
	v_add_f32_e32 v200, v200, v87
	s_setprio 1
	ds_read_b128 v[2:5], v176 offset:24576
	ds_read_b128 v[6:9], v176 offset:28672
	ds_read_b128 v[10:13], v176 offset:32768
	ds_read_b128 v[238:241], v176 offset:36864
	v_cvt_pk_bf16_f32 v80, v80, v81
	v_cvt_pk_bf16_f32 v81, v82, v83
	v_cvt_pk_bf16_f32 v82, v84, v85
	v_cvt_pk_bf16_f32 v83, v86, v87
	v_add_f32_e32 v200, v200, v88
	v_add_f32_e32 v200, v200, v89
	s_waitcnt lgkmcnt(8)
	v_mfma_f32_32x32x16_bf16 v[64:79], v[80:83], v[144:147], v[64:79]
	v_med3_f32 v184, v184, s4, v236
	v_exp_f32_e32 v184, v184
	v_med3_f32 v185, v185, s4, v236
	v_exp_f32_e32 v185, v185
	v_add_f32_e32 v200, v200, v90
	v_add_f32_e32 v200, v200, v91
	v_mfma_f32_32x32x16_bf16 v[48:63], v[80:83], v[148:151], v[48:63]
	v_med3_f32 v186, v186, s4, v236
	v_exp_f32_e32 v186, v186
	v_med3_f32 v187, v187, s4, v236
	v_exp_f32_e32 v187, v187
	v_add_f32_e32 v200, v200, v92
	v_add_f32_e32 v200, v200, v93
	v_mfma_f32_32x32x16_bf16 v[32:47], v[80:83], v[152:155], v[32:47]
	v_med3_f32 v188, v188, s4, v236
	v_exp_f32_e32 v188, v188
	v_med3_f32 v189, v189, s4, v236
	v_exp_f32_e32 v189, v189
	v_add_f32_e32 v200, v200, v94
	v_add_f32_e32 v200, v200, v95
	v_mfma_f32_32x32x16_bf16 v[16:31], v[80:83], v[156:159], v[16:31]
	v_med3_f32 v190, v190, s4, v236
	v_exp_f32_e32 v190, v190
	v_med3_f32 v191, v191, s4, v236
	v_exp_f32_e32 v191, v191
	v_cvt_pk_bf16_f32 v84, v88, v89
	v_cvt_pk_bf16_f32 v85, v90, v91
	v_cvt_pk_bf16_f32 v86, v92, v93
	v_cvt_pk_bf16_f32 v87, v94, v95
	ds_read_b128 v[144:147], v177 offset:24576
	ds_read_b128 v[148:151], v177 offset:28672
	ds_read_b128 v[152:155], v177 offset:32768
	ds_read_b128 v[156:159], v177 offset:36864
	s_waitcnt lgkmcnt(8)
	v_mfma_f32_32x32x16_bf16 v[64:79], v[84:87], v[160:163], v[64:79]
	v_med3_f32 v192, v192, s4, v236
	v_exp_f32_e32 v192, v192
	v_med3_f32 v193, v193, s4, v236
	v_exp_f32_e32 v193, v193
	v_add_f32_e32 v201, v184, v185
	v_add_f32_e32 v201, v201, v186
	v_mfma_f32_32x32x16_bf16 v[48:63], v[84:87], v[164:167], v[48:63]
	v_med3_f32 v194, v194, s4, v236
	v_exp_f32_e32 v194, v194
	v_med3_f32 v195, v195, s4, v236
	v_exp_f32_e32 v195, v195
	v_add_f32_e32 v201, v201, v187
	v_add_f32_e32 v201, v201, v188
	v_mfma_f32_32x32x16_bf16 v[32:47], v[84:87], v[168:171], v[32:47]
	v_med3_f32 v196, v196, s4, v236
	v_exp_f32_e32 v196, v196
	v_med3_f32 v197, v197, s4, v236
	v_exp_f32_e32 v197, v197
	v_add_f32_e32 v201, v201, v189
	v_mfma_f32_32x32x16_bf16 v[16:31], v[84:87], v[172:175], v[16:31]
	v_med3_f32 v198, v198, s4, v236
	v_exp_f32_e32 v198, v198
	v_med3_f32 v199, v199, s4, v236
	v_exp_f32_e32 v199, v199
	v_add_f32_e32 v201, v201, v190
	v_cvt_pk_bf16_f32 v184, v184, v185
	v_cvt_pk_bf16_f32 v185, v186, v187
	v_cvt_pk_bf16_f32 v186, v188, v189
	v_cvt_pk_bf16_f32 v187, v190, v191
	v_add_f32_e32 v201, v201, v191
	s_setprio 0
	s_waitcnt lgkmcnt(4)
	v_mfma_f32_32x32x16_bf16 v[64:79], v[184:187], v[2:5], v[64:79]
	v_add_f32_e32 v201, v201, v192
	v_add_f32_e32 v201, v201, v193
	v_add_f32_e32 v201, v201, v194
	v_mfma_f32_32x32x16_bf16 v[48:63], v[184:187], v[6:9], v[48:63]
	v_add_f32_e32 v201, v201, v195
	v_add_f32_e32 v201, v201, v196
	v_add_f32_e32 v201, v201, v197
	v_mfma_f32_32x32x16_bf16 v[32:47], v[184:187], v[10:13], v[32:47]
	v_add_f32_e32 v201, v201, v198
	v_add_f32_e32 v201, v201, v199
	v_cvt_pk_bf16_f32 v188, v192, v193
	v_cvt_pk_bf16_f32 v189, v194, v195
	v_cvt_pk_bf16_f32 v190, v196, v197
	v_cvt_pk_bf16_f32 v191, v198, v199
	v_mfma_f32_32x32x16_bf16 v[16:31], v[184:187], v[238:241], v[16:31]
	v_add_f32_e32 v200, v200, v201
	v_add_f32_e32 v218, v218, v200
	s_waitcnt lgkmcnt(0)
	v_mfma_f32_32x32x16_bf16 v[64:79], v[188:191], v[144:147], v[64:79]
	v_mfma_f32_32x32x16_bf16 v[48:63], v[188:191], v[148:151], v[48:63]
	v_mfma_f32_32x32x16_bf16 v[32:47], v[188:191], v[152:155], v[32:47]
	v_mfma_f32_32x32x16_bf16 v[16:31], v[188:191], v[156:159], v[16:31]
	s_waitcnt vmcnt(5) lgkmcnt(0)
	s_branch .LBB0_530
.Lat1_nodma:
	s_setprio 3
	v_mov_b32_e32 v206, v217
	s_mul_i32 s10, s0, 0xa000
	v_lshlrev_b32_e32 v209, 3, v206
	v_lshrrev_b32_e32 v207, 1, v206
	v_lshlrev_b32_e32 v208, 7, v206
	v_and_b32_e32 v209, 8, v209
	v_ashrrev_i32_e32 v206, 5, v206
	v_add_u32_e32 v206, v209, v206
	v_and_b32_e32 v208, 0xf00, v208
	v_bitop3_b32 v209, v206, v207, 7 bitop3:0x78
	v_add_u32_e32 v210, 2, v206
	v_add_u32_e32 v211, 4, v206
	v_add_u32_e32 v206, 6, v206
	v_add_u32_e32 v208, s10, v208
	v_bitop3_b32 v210, v210, v207, 7 bitop3:0x78
	v_bitop3_b32 v211, v211, v207, 7 bitop3:0x78
	v_bitop3_b32 v206, v206, v207, 7 bitop3:0x78
	v_lshl_add_u32 v14, v209, 4, v208
	v_lshl_add_u32 v15, v210, 4, v208
	v_lshl_add_u32 v176, v211, 4, v208
	v_lshl_add_u32 v177, v206, 4, v208
	ds_read_b128 v[144:147], v14 offset:0
	ds_read_b128 v[148:151], v15 offset:0
	ds_read_b128 v[152:155], v176 offset:0
	ds_read_b128 v[156:159], v177 offset:0
	ds_read_b128 v[160:163], v14 offset:8192
	ds_read_b128 v[164:167], v15 offset:8192
	ds_read_b128 v[168:171], v176 offset:8192
	ds_read_b128 v[172:175], v177 offset:8192
	ds_read_b128 v[2:5], v14 offset:16384
	ds_read_b128 v[6:9], v15 offset:16384
	ds_read_b128 v[10:13], v176 offset:16384
	ds_read_b128 v[238:241], v177 offset:16384
	s_waitcnt lgkmcnt(8)
	v_mfma_f32_32x32x16_bf16 v[80:95], v[144:147], v[132:135], 0
	v_mfma_f32_32x32x16_bf16 v[80:95], v[148:151], v[128:131], v[80:95]
	v_mfma_f32_32x32x16_bf16 v[80:95], v[152:155], v[124:127], v[80:95]
	v_mfma_f32_32x32x16_bf16 v[80:95], v[156:159], v[120:123], v[80:95]
	ds_read_b128 v[144:147], v14 offset:4096
	ds_read_b128 v[148:151], v15 offset:4096
	ds_read_b128 v[152:155], v176 offset:4096
	ds_read_b128 v[156:159], v177 offset:4096
	s_waitcnt lgkmcnt(8)
	v_mfma_f32_32x32x16_bf16 v[80:95], v[160:163], v[116:119], v[80:95]
	v_mfma_f32_32x32x16_bf16 v[80:95], v[164:167], v[112:115], v[80:95]
	v_mfma_f32_32x32x16_bf16 v[80:95], v[168:171], v[108:111], v[80:95]
	v_mfma_f32_32x32x16_bf16 v[80:95], v[172:175], v[104:107], v[80:95]
	ds_read_b128 v[160:163], v14 offset:12288
	ds_read_b128 v[164:167], v15 offset:12288
	ds_read_b128 v[168:171], v176 offset:12288
	ds_read_b128 v[172:175], v177 offset:12288
	s_waitcnt lgkmcnt(8)
	v_mfma_f32_32x32x16_bf16 v[80:95], v[2:5], v[100:103], v[80:95]
	v_mfma_f32_32x32x16_bf16 v[80:95], v[6:9], v[140:143], v[80:95]
	v_mfma_f32_32x32x16_bf16 v[80:95], v[10:13], v[96:99], v[80:95]
	v_mfma_f32_32x32x16_bf16 v[80:95], v[238:241], v[136:139], v[80:95]
	s_setprio 2
	ds_read_b128 v[2:5], v14 offset:20480
	ds_read_b128 v[6:9], v15 offset:20480
	ds_read_b128 v[10:13], v176 offset:20480
	ds_read_b128 v[238:241], v177 offset:20480
	s_waitcnt lgkmcnt(8)
	v_mfma_f32_32x32x16_bf16 v[184:199], v[144:147], v[132:135], 0
	v_mfma_f32_32x32x16_bf16 v[184:199], v[148:151], v[128:131], v[184:199]
	v_mfma_f32_32x32x16_bf16 v[184:199], v[152:155], v[124:127], v[184:199]
	v_mfma_f32_32x32x16_bf16 v[184:199], v[156:159], v[120:123], v[184:199]
	ds_read_b128 v[144:147], v14 offset:24576
	ds_read_b128 v[148:151], v14 offset:28672
	ds_read_b128 v[152:155], v14 offset:32768
	ds_read_b128 v[156:159], v14 offset:36864
	s_waitcnt lgkmcnt(8)
	v_mfma_f32_32x32x16_bf16 v[184:199], v[160:163], v[116:119], v[184:199]
	v_med3_f32 v80, v80, s4, v236
	v_exp_f32_e32 v80, v80
	v_med3_f32 v81, v81, s4, v236
	v_exp_f32_e32 v81, v81
	v_mfma_f32_32x32x16_bf16 v[184:199], v[164:167], v[112:115], v[184:199]
	v_med3_f32 v82, v82, s4, v236
	v_exp_f32_e32 v82, v82
	v_med3_f32 v83, v83, s4, v236
	v_exp_f32_e32 v83, v83
	v_mfma_f32_32x32x16_bf16 v[184:199], v[168:171], v[108:111], v[184:199]
	v_med3_f32 v84, v84, s4, v236
	v_exp_f32_e32 v84, v84
	v_med3_f32 v85, v85, s4, v236
	v_exp_f32_e32 v85, v85
	v_mfma_f32_32x32x16_bf16 v[184:199], v[172:175], v[104:107], v[184:199]
	v_med3_f32 v86, v86, s4, v236
	v_exp_f32_e32 v86, v86
	v_med3_f32 v87, v87, s4, v236
	v_exp_f32_e32 v87, v87
	ds_read_b128 v[160:163], v15 offset:24576
	ds_read_b128 v[164:167], v15 offset:28672
	ds_read_b128 v[168:171], v15 offset:32768
	ds_read_b128 v[172:175], v15 offset:36864
	s_waitcnt lgkmcnt(8)
	v_mfma_f32_32x32x16_bf16 v[184:199], v[2:5], v[100:103], v[184:199]
	v_med3_f32 v88, v88, s4, v236
	v_exp_f32_e32 v88, v88
	v_med3_f32 v89, v89, s4, v236
	v_exp_f32_e32 v89, v89
	v_add_f32_e32 v200, v80, v81
	v_add_f32_e32 v200, v200, v82
	v_mfma_f32_32x32x16_bf16 v[184:199], v[6:9], v[140:143], v[184:199]
	v_med3_f32 v90, v90, s4, v236
	v_exp_f32_e32 v90, v90
	v_med3_f32 v91, v91, s4, v236
	v_exp_f32_e32 v91, v91
	v_add_f32_e32 v200, v200, v83
	v_add_f32_e32 v200, v200, v84
	v_mfma_f32_32x32x16_bf16 v[184:199], v[10:13], v[96:99], v[184:199]
	v_med3_f32 v92, v92, s4, v236
	v_exp_f32_e32 v92, v92
	v_med3_f32 v93, v93, s4, v236
	v_exp_f32_e32 v93, v93
	v_add_f32_e32 v200, v200, v85
	v_add_f32_e32 v200, v200, v86
	v_mfma_f32_32x32x16_bf16 v[184:199], v[238:241], v[136:139], v[184:199]
	v_med3_f32 v94, v94, s4, v236
	v_exp_f32_e32 v94, v94
	v_med3_f32 v95, v95, s4, v236
	v_exp_f32_e32 v95, v95
	v_add_f32_e32 v200, v200, v87
	s_setprio 1
	ds_read_b128 v[2:5], v176 offset:24576
	ds_read_b128 v[6:9], v176 offset:28672
	ds_read_b128 v[10:13], v176 offset:32768
	ds_read_b128 v[238:241], v176 offset:36864
	v_cvt_pk_bf16_f32 v80, v80, v81
	v_cvt_pk_bf16_f32 v81, v82, v83
	v_cvt_pk_bf16_f32 v82, v84, v85
	v_cvt_pk_bf16_f32 v83, v86, v87
	v_add_f32_e32 v200, v200, v88
	v_add_f32_e32 v200, v200, v89
	s_waitcnt lgkmcnt(8)
	v_mfma_f32_32x32x16_bf16 v[64:79], v[80:83], v[144:147], v[64:79]
	v_med3_f32 v184, v184, s4, v236
	v_exp_f32_e32 v184, v184
	v_med3_f32 v185, v185, s4, v236
	v_exp_f32_e32 v185, v185
	v_add_f32_e32 v200, v200, v90
	v_add_f32_e32 v200, v200, v91
	v_mfma_f32_32x32x16_bf16 v[48:63], v[80:83], v[148:151], v[48:63]
	v_med3_f32 v186, v186, s4, v236
	v_exp_f32_e32 v186, v186
	v_med3_f32 v187, v187, s4, v236
	v_exp_f32_e32 v187, v187
	v_add_f32_e32 v200, v200, v92
	v_add_f32_e32 v200, v200, v93
	v_mfma_f32_32x32x16_bf16 v[32:47], v[80:83], v[152:155], v[32:47]
	v_med3_f32 v188, v188, s4, v236
	v_exp_f32_e32 v188, v188
	v_med3_f32 v189, v189, s4, v236
	v_exp_f32_e32 v189, v189
	v_add_f32_e32 v200, v200, v94
	v_add_f32_e32 v200, v200, v95
	v_mfma_f32_32x32x16_bf16 v[16:31], v[80:83], v[156:159], v[16:31]
	v_med3_f32 v190, v190, s4, v236
	v_exp_f32_e32 v190, v190
	v_med3_f32 v191, v191, s4, v236
	v_exp_f32_e32 v191, v191
	v_cvt_pk_bf16_f32 v84, v88, v89
	v_cvt_pk_bf16_f32 v85, v90, v91
	v_cvt_pk_bf16_f32 v86, v92, v93
	v_cvt_pk_bf16_f32 v87, v94, v95
	ds_read_b128 v[144:147], v177 offset:24576
	ds_read_b128 v[148:151], v177 offset:28672
	ds_read_b128 v[152:155], v177 offset:32768
	ds_read_b128 v[156:159], v177 offset:36864
	s_waitcnt lgkmcnt(8)
	v_mfma_f32_32x32x16_bf16 v[64:79], v[84:87], v[160:163], v[64:79]
	v_med3_f32 v192, v192, s4, v236
	v_exp_f32_e32 v192, v192
	v_med3_f32 v193, v193, s4, v236
	v_exp_f32_e32 v193, v193
	v_add_f32_e32 v201, v184, v185
	v_add_f32_e32 v201, v201, v186
	v_mfma_f32_32x32x16_bf16 v[48:63], v[84:87], v[164:167], v[48:63]
	v_med3_f32 v194, v194, s4, v236
	v_exp_f32_e32 v194, v194
	v_med3_f32 v195, v195, s4, v236
	v_exp_f32_e32 v195, v195
	v_add_f32_e32 v201, v201, v187
	v_add_f32_e32 v201, v201, v188
	v_mfma_f32_32x32x16_bf16 v[32:47], v[84:87], v[168:171], v[32:47]
	v_med3_f32 v196, v196, s4, v236
	v_exp_f32_e32 v196, v196
	v_med3_f32 v197, v197, s4, v236
	v_exp_f32_e32 v197, v197
	v_add_f32_e32 v201, v201, v189
	v_mfma_f32_32x32x16_bf16 v[16:31], v[84:87], v[172:175], v[16:31]
	v_med3_f32 v198, v198, s4, v236
	v_exp_f32_e32 v198, v198
	v_med3_f32 v199, v199, s4, v236
	v_exp_f32_e32 v199, v199
	v_add_f32_e32 v201, v201, v190
	v_cvt_pk_bf16_f32 v184, v184, v185
	v_cvt_pk_bf16_f32 v185, v186, v187
	v_cvt_pk_bf16_f32 v186, v188, v189
	v_cvt_pk_bf16_f32 v187, v190, v191
	v_add_f32_e32 v201, v201, v191
	s_setprio 0
	s_waitcnt lgkmcnt(4)
	v_mfma_f32_32x32x16_bf16 v[64:79], v[184:187], v[2:5], v[64:79]
	v_add_f32_e32 v201, v201, v192
	v_add_f32_e32 v201, v201, v193
	v_add_f32_e32 v201, v201, v194
	v_mfma_f32_32x32x16_bf16 v[48:63], v[184:187], v[6:9], v[48:63]
	v_add_f32_e32 v201, v201, v195
	v_add_f32_e32 v201, v201, v196
	v_add_f32_e32 v201, v201, v197
	v_mfma_f32_32x32x16_bf16 v[32:47], v[184:187], v[10:13], v[32:47]
	v_add_f32_e32 v201, v201, v198
	v_add_f32_e32 v201, v201, v199
	v_cvt_pk_bf16_f32 v188, v192, v193
	v_cvt_pk_bf16_f32 v189, v194, v195
	v_cvt_pk_bf16_f32 v190, v196, v197
	v_cvt_pk_bf16_f32 v191, v198, v199
	v_mfma_f32_32x32x16_bf16 v[16:31], v[184:187], v[238:241], v[16:31]
	v_add_f32_e32 v200, v200, v201
	v_add_f32_e32 v218, v218, v200
	s_waitcnt lgkmcnt(0)
	v_mfma_f32_32x32x16_bf16 v[64:79], v[188:191], v[144:147], v[64:79]
	v_mfma_f32_32x32x16_bf16 v[48:63], v[188:191], v[148:151], v[48:63]
	v_mfma_f32_32x32x16_bf16 v[32:47], v[188:191], v[152:155], v[32:47]
	v_mfma_f32_32x32x16_bf16 v[16:31], v[188:191], v[156:159], v[16:31]
	s_waitcnt vmcnt(0) lgkmcnt(0)
	s_branch .LBB0_530

.LBB0_574:
	s_add_i32 s10, s33, 2
	s_cmp_ge_i32 s10, s21
	s_cselect_b64 s[22:23], -1, 0
	s_mov_b64 s[34:35], -1
	s_cmp_gt_i32 s33, s9
	s_cbranch_scc1 .Lat2_skip
	s_and_b64 vcc, exec, s[22:23]
	s_cbranch_vccnz .Lat2_nodma
	s_setprio 3
	v_mov_b32_e32 v208, v222
	s_mul_i32 s10, s28, 0xa000
	v_lshlrev_b32_e32 v211, 3, v208
	v_lshrrev_b32_e32 v209, 1, v208
	v_lshlrev_b32_e32 v210, 7, v208
	v_and_b32_e32 v211, 8, v211
	v_ashrrev_i32_e32 v208, 5, v208
	v_add_u32_e32 v208, v211, v208
	v_and_b32_e32 v210, 0xf00, v210
	v_bitop3_b32 v211, v208, v209, 7 bitop3:0x78
	v_add_u32_e32 v212, 2, v208
	v_add_u32_e32 v213, 4, v208
	v_add_u32_e32 v208, 6, v208
	v_add_u32_e32 v210, s10, v210
	v_bitop3_b32 v212, v212, v209, 7 bitop3:0x78
	v_bitop3_b32 v213, v213, v209, 7 bitop3:0x78
	v_bitop3_b32 v208, v208, v209, 7 bitop3:0x78
	v_lshl_add_u32 v198, v211, 4, v210
	v_lshl_add_u32 v199, v212, 4, v210
	v_lshl_add_u32 v200, v213, 4, v210
	v_lshl_add_u32 v201, v208, 4, v210
	ds_read_b128 v[130:133], v198 offset:0
	ds_read_b128 v[134:137], v199 offset:0
	ds_read_b128 v[138:141], v200 offset:0
	ds_read_b128 v[142:145], v201 offset:0
	ds_read_b128 v[146:149], v198 offset:8192
	ds_read_b128 v[150:153], v199 offset:8192
	ds_read_b128 v[154:157], v200 offset:8192
	ds_read_b128 v[158:161], v201 offset:8192
	ds_read_b128 v[162:165], v198 offset:16384
	ds_read_b128 v[166:169], v199 offset:16384
	ds_read_b128 v[170:173], v200 offset:16384
	ds_read_b128 v[176:179], v201 offset:16384
	v_mad_u64_u32 v[204:205], s[10:11], s86, v228, v[174:175]
	s_mul_i32 s10, s7, 0xa000
	s_add_i32 s10, s0, s10
	s_mov_b32 m0, s10
	v_lshl_add_u64 v[206:207], v[204:205], 0, s[94:95]
	global_load_lds_dwordx4 v[204:205], off
	s_add_i32 m0, s10, 0x2000
	v_lshl_add_u64 v[204:205], v[204:205], 0, s[96:97]
	global_load_lds_dwordx4 v[206:207], off
	s_waitcnt lgkmcnt(8)
	v_mfma_f32_32x32x16_bf16 v[66:81], v[130:133], v[118:121], 0
	s_add_i32 m0, s10, 0x4000
	v_mfma_f32_32x32x16_bf16 v[66:81], v[134:137], v[114:117], v[66:81]
	global_load_lds_dwordx4 v[204:205], off
	v_lshl_add_u64 v[204:205], s[86:87], 1, v[180:181]
	s_add_i32 m0, s10, 0x6000
	v_mfma_f32_32x32x16_bf16 v[66:81], v[138:141], v[110:113], v[66:81]
	global_load_lds_dwordx4 v[204:205], off
	v_lshl_add_u64 v[204:205], v[204:205], 0, s[92:93]
	s_add_i32 m0, s10, 0x8000
	v_mfma_f32_32x32x16_bf16 v[66:81], v[142:145], v[106:109], v[66:81]
	global_load_lds_dwordx4 v[204:205], off
	ds_read_b128 v[130:133], v198 offset:4096
	ds_read_b128 v[134:137], v199 offset:4096
	ds_read_b128 v[138:141], v200 offset:4096
	ds_read_b128 v[142:145], v201 offset:4096
	s_waitcnt lgkmcnt(8)
	v_mfma_f32_32x32x16_bf16 v[66:81], v[146:149], v[102:105], v[66:81]
	v_mfma_f32_32x32x16_bf16 v[66:81], v[150:153], v[98:101], v[66:81]
	v_mfma_f32_32x32x16_bf16 v[66:81], v[154:157], v[94:97], v[66:81]
	v_mfma_f32_32x32x16_bf16 v[66:81], v[158:161], v[90:93], v[66:81]
	ds_read_b128 v[146:149], v198 offset:12288
	ds_read_b128 v[150:153], v199 offset:12288
	ds_read_b128 v[154:157], v200 offset:12288
	ds_read_b128 v[158:161], v201 offset:12288
	s_waitcnt lgkmcnt(8)
	v_mfma_f32_32x32x16_bf16 v[66:81], v[162:165], v[86:89], v[66:81]
	v_mfma_f32_32x32x16_bf16 v[66:81], v[166:169], v[126:129], v[66:81]
	v_mfma_f32_32x32x16_bf16 v[66:81], v[170:173], v[82:85], v[66:81]
	v_mfma_f32_32x32x16_bf16 v[66:81], v[176:179], v[122:125], v[66:81]
	s_setprio 2
	ds_read_b128 v[162:165], v198 offset:20480
	ds_read_b128 v[166:169], v199 offset:20480
	ds_read_b128 v[170:173], v200 offset:20480
	ds_read_b128 v[176:179], v201 offset:20480
	s_waitcnt lgkmcnt(8)
	v_mfma_f32_32x32x16_bf16 v[182:197], v[130:133], v[118:121], 0
	v_mfma_f32_32x32x16_bf16 v[182:197], v[134:137], v[114:117], v[182:197]
	v_mfma_f32_32x32x16_bf16 v[182:197], v[138:141], v[110:113], v[182:197]
	v_mfma_f32_32x32x16_bf16 v[182:197], v[142:145], v[106:109], v[182:197]
	ds_read_b128 v[130:133], v198 offset:24576
	ds_read_b128 v[134:137], v198 offset:28672
	ds_read_b128 v[138:141], v198 offset:32768
	ds_read_b128 v[142:145], v198 offset:36864
	s_waitcnt lgkmcnt(8)
	v_mfma_f32_32x32x16_bf16 v[182:197], v[146:149], v[102:105], v[182:197]
	v_med3_f32 v66, v66, s4, v236
	v_exp_f32_e32 v66, v66
	v_med3_f32 v67, v67, s4, v236
	v_exp_f32_e32 v67, v67
	v_mfma_f32_32x32x16_bf16 v[182:197], v[150:153], v[98:101], v[182:197]
	v_med3_f32 v68, v68, s4, v236
	v_exp_f32_e32 v68, v68
	v_med3_f32 v69, v69, s4, v236
	v_exp_f32_e32 v69, v69
	v_mfma_f32_32x32x16_bf16 v[182:197], v[154:157], v[94:97], v[182:197]
	v_med3_f32 v70, v70, s4, v236
	v_exp_f32_e32 v70, v70
	v_med3_f32 v71, v71, s4, v236
	v_exp_f32_e32 v71, v71
	v_mfma_f32_32x32x16_bf16 v[182:197], v[158:161], v[90:93], v[182:197]
	v_med3_f32 v72, v72, s4, v236
	v_exp_f32_e32 v72, v72
	v_med3_f32 v73, v73, s4, v236
	v_exp_f32_e32 v73, v73
	ds_read_b128 v[146:149], v199 offset:24576
	ds_read_b128 v[150:153], v199 offset:28672
	ds_read_b128 v[154:157], v199 offset:32768
	ds_read_b128 v[158:161], v199 offset:36864
	s_waitcnt lgkmcnt(8)
	v_mfma_f32_32x32x16_bf16 v[182:197], v[162:165], v[86:89], v[182:197]
	v_med3_f32 v74, v74, s4, v236
	v_exp_f32_e32 v74, v74
	v_med3_f32 v75, v75, s4, v236
	v_exp_f32_e32 v75, v75
	v_add_f32_e32 v202, v66, v67
	v_add_f32_e32 v202, v202, v68
	v_mfma_f32_32x32x16_bf16 v[182:197], v[166:169], v[126:129], v[182:197]
	v_med3_f32 v76, v76, s4, v236
	v_exp_f32_e32 v76, v76
	v_med3_f32 v77, v77, s4, v236
	v_exp_f32_e32 v77, v77
	v_add_f32_e32 v202, v202, v69
	v_add_f32_e32 v202, v202, v70
	v_mfma_f32_32x32x16_bf16 v[182:197], v[170:173], v[82:85], v[182:197]
	v_med3_f32 v78, v78, s4, v236
	v_exp_f32_e32 v78, v78
	v_med3_f32 v79, v79, s4, v236
	v_exp_f32_e32 v79, v79
	v_add_f32_e32 v202, v202, v71
	v_add_f32_e32 v202, v202, v72
	v_mfma_f32_32x32x16_bf16 v[182:197], v[176:179], v[122:125], v[182:197]
	v_med3_f32 v80, v80, s4, v236
	v_exp_f32_e32 v80, v80
	v_med3_f32 v81, v81, s4, v236
	v_exp_f32_e32 v81, v81
	v_add_f32_e32 v202, v202, v73
	s_setprio 1
	ds_read_b128 v[162:165], v200 offset:24576
	ds_read_b128 v[166:169], v200 offset:28672
	ds_read_b128 v[170:173], v200 offset:32768
	ds_read_b128 v[176:179], v200 offset:36864
	v_cvt_pk_bf16_f32 v66, v66, v67
	v_cvt_pk_bf16_f32 v67, v68, v69
	v_cvt_pk_bf16_f32 v68, v70, v71
	v_cvt_pk_bf16_f32 v69, v72, v73
	v_add_f32_e32 v202, v202, v74
	v_add_f32_e32 v202, v202, v75
	s_waitcnt lgkmcnt(8)
	v_mfma_f32_32x32x16_bf16 v[50:65], v[66:69], v[130:133], v[50:65]
	v_med3_f32 v182, v182, s4, v236
	v_exp_f32_e32 v182, v182
	v_med3_f32 v183, v183, s4, v236
	v_exp_f32_e32 v183, v183
	v_add_f32_e32 v202, v202, v76
	v_add_f32_e32 v202, v202, v77
	v_mfma_f32_32x32x16_bf16 v[34:49], v[66:69], v[134:137], v[34:49]
	v_med3_f32 v184, v184, s4, v236
	v_exp_f32_e32 v184, v184
	v_med3_f32 v185, v185, s4, v236
	v_exp_f32_e32 v185, v185
	v_add_f32_e32 v202, v202, v78
	v_add_f32_e32 v202, v202, v79
	v_mfma_f32_32x32x16_bf16 v[18:33], v[66:69], v[138:141], v[18:33]
	v_med3_f32 v186, v186, s4, v236
	v_exp_f32_e32 v186, v186
	v_med3_f32 v187, v187, s4, v236
	v_exp_f32_e32 v187, v187
	v_add_f32_e32 v202, v202, v80
	v_add_f32_e32 v202, v202, v81
	v_mfma_f32_32x32x16_bf16 v[2:17], v[66:69], v[142:145], v[2:17]
	v_med3_f32 v188, v188, s4, v236
	v_exp_f32_e32 v188, v188
	v_med3_f32 v189, v189, s4, v236
	v_exp_f32_e32 v189, v189
	v_cvt_pk_bf16_f32 v70, v74, v75
	v_cvt_pk_bf16_f32 v71, v76, v77
	v_cvt_pk_bf16_f32 v72, v78, v79
	v_cvt_pk_bf16_f32 v73, v80, v81
	ds_read_b128 v[130:133], v201 offset:24576
	ds_read_b128 v[134:137], v201 offset:28672
	ds_read_b128 v[138:141], v201 offset:32768
	ds_read_b128 v[142:145], v201 offset:36864
	s_waitcnt lgkmcnt(8)
	v_mfma_f32_32x32x16_bf16 v[50:65], v[70:73], v[146:149], v[50:65]
	v_med3_f32 v190, v190, s4, v236
	v_exp_f32_e32 v190, v190
	v_med3_f32 v191, v191, s4, v236
	v_exp_f32_e32 v191, v191
	v_add_f32_e32 v203, v182, v183
	v_add_f32_e32 v203, v203, v184
	v_mfma_f32_32x32x16_bf16 v[34:49], v[70:73], v[150:153], v[34:49]
	v_med3_f32 v192, v192, s4, v236
	v_exp_f32_e32 v192, v192
	v_med3_f32 v193, v193, s4, v236
	v_exp_f32_e32 v193, v193
	v_add_f32_e32 v203, v203, v185
	v_add_f32_e32 v203, v203, v186
	v_mfma_f32_32x32x16_bf16 v[18:33], v[70:73], v[154:157], v[18:33]
	v_med3_f32 v194, v194, s4, v236
	v_exp_f32_e32 v194, v194
	v_med3_f32 v195, v195, s4, v236
	v_exp_f32_e32 v195, v195
	v_add_f32_e32 v203, v203, v187
	v_mfma_f32_32x32x16_bf16 v[2:17], v[70:73], v[158:161], v[2:17]
	v_med3_f32 v196, v196, s4, v236
	v_exp_f32_e32 v196, v196
	v_med3_f32 v197, v197, s4, v236
	v_exp_f32_e32 v197, v197
	v_add_f32_e32 v203, v203, v188
	v_cvt_pk_bf16_f32 v182, v182, v183
	v_cvt_pk_bf16_f32 v183, v184, v185
	v_cvt_pk_bf16_f32 v184, v186, v187
	v_cvt_pk_bf16_f32 v185, v188, v189
	v_add_f32_e32 v203, v203, v189
	s_setprio 0
	s_waitcnt lgkmcnt(4)
	v_mfma_f32_32x32x16_bf16 v[50:65], v[182:185], v[162:165], v[50:65]
	v_add_f32_e32 v203, v203, v190
	v_add_f32_e32 v203, v203, v191
	v_add_f32_e32 v203, v203, v192
	v_mfma_f32_32x32x16_bf16 v[34:49], v[182:185], v[166:169], v[34:49]
	v_add_f32_e32 v203, v203, v193
	v_add_f32_e32 v203, v203, v194
	v_add_f32_e32 v203, v203, v195
	v_mfma_f32_32x32x16_bf16 v[18:33], v[182:185], v[170:173], v[18:33]
	v_add_f32_e32 v203, v203, v196
	v_add_f32_e32 v203, v203, v197
	v_cvt_pk_bf16_f32 v186, v190, v191
	v_cvt_pk_bf16_f32 v187, v192, v193
	v_cvt_pk_bf16_f32 v188, v194, v195
	v_cvt_pk_bf16_f32 v189, v196, v197
	v_mfma_f32_32x32x16_bf16 v[2:17], v[182:185], v[176:179], v[2:17]
	v_add_f32_e32 v202, v202, v203
	v_add_f32_e32 v0, v0, v202
	s_waitcnt lgkmcnt(0)
	v_mfma_f32_32x32x16_bf16 v[50:65], v[186:189], v[130:133], v[50:65]
	v_mfma_f32_32x32x16_bf16 v[34:49], v[186:189], v[134:137], v[34:49]
	v_mfma_f32_32x32x16_bf16 v[18:33], v[186:189], v[138:141], v[18:33]
	v_mfma_f32_32x32x16_bf16 v[2:17], v[186:189], v[142:145], v[2:17]
	s_waitcnt vmcnt(5) lgkmcnt(0)
	s_branch .LBB0_573
.Lat2_nodma:
	s_setprio 3
	v_mov_b32_e32 v208, v222
	s_mul_i32 s10, s28, 0xa000
	v_lshlrev_b32_e32 v211, 3, v208
	v_lshrrev_b32_e32 v209, 1, v208
	v_lshlrev_b32_e32 v210, 7, v208
	v_and_b32_e32 v211, 8, v211
	v_ashrrev_i32_e32 v208, 5, v208
	v_add_u32_e32 v208, v211, v208
	v_and_b32_e32 v210, 0xf00, v210
	v_bitop3_b32 v211, v208, v209, 7 bitop3:0x78
	v_add_u32_e32 v212, 2, v208
	v_add_u32_e32 v213, 4, v208
	v_add_u32_e32 v208, 6, v208
	v_add_u32_e32 v210, s10, v210
	v_bitop3_b32 v212, v212, v209, 7 bitop3:0x78
	v_bitop3_b32 v213, v213, v209, 7 bitop3:0x78
	v_bitop3_b32 v208, v208, v209, 7 bitop3:0x78
	v_lshl_add_u32 v198, v211, 4, v210
	v_lshl_add_u32 v199, v212, 4, v210
	v_lshl_add_u32 v200, v213, 4, v210
	v_lshl_add_u32 v201, v208, 4, v210
	ds_read_b128 v[130:133], v198 offset:0
	ds_read_b128 v[134:137], v199 offset:0
	ds_read_b128 v[138:141], v200 offset:0
	ds_read_b128 v[142:145], v201 offset:0
	ds_read_b128 v[146:149], v198 offset:8192
	ds_read_b128 v[150:153], v199 offset:8192
	ds_read_b128 v[154:157], v200 offset:8192
	ds_read_b128 v[158:161], v201 offset:8192
	ds_read_b128 v[162:165], v198 offset:16384
	ds_read_b128 v[166:169], v199 offset:16384
	ds_read_b128 v[170:173], v200 offset:16384
	ds_read_b128 v[176:179], v201 offset:16384
	s_waitcnt lgkmcnt(8)
	v_mfma_f32_32x32x16_bf16 v[66:81], v[130:133], v[118:121], 0
	v_mfma_f32_32x32x16_bf16 v[66:81], v[134:137], v[114:117], v[66:81]
	v_mfma_f32_32x32x16_bf16 v[66:81], v[138:141], v[110:113], v[66:81]
	v_mfma_f32_32x32x16_bf16 v[66:81], v[142:145], v[106:109], v[66:81]
	ds_read_b128 v[130:133], v198 offset:4096
	ds_read_b128 v[134:137], v199 offset:4096
	ds_read_b128 v[138:141], v200 offset:4096
	ds_read_b128 v[142:145], v201 offset:4096
	s_waitcnt lgkmcnt(8)
	v_mfma_f32_32x32x16_bf16 v[66:81], v[146:149], v[102:105], v[66:81]
	v_mfma_f32_32x32x16_bf16 v[66:81], v[150:153], v[98:101], v[66:81]
	v_mfma_f32_32x32x16_bf16 v[66:81], v[154:157], v[94:97], v[66:81]
	v_mfma_f32_32x32x16_bf16 v[66:81], v[158:161], v[90:93], v[66:81]
	ds_read_b128 v[146:149], v198 offset:12288
	ds_read_b128 v[150:153], v199 offset:12288
	ds_read_b128 v[154:157], v200 offset:12288
	ds_read_b128 v[158:161], v201 offset:12288
	s_waitcnt lgkmcnt(8)
	v_mfma_f32_32x32x16_bf16 v[66:81], v[162:165], v[86:89], v[66:81]
	v_mfma_f32_32x32x16_bf16 v[66:81], v[166:169], v[126:129], v[66:81]
	v_mfma_f32_32x32x16_bf16 v[66:81], v[170:173], v[82:85], v[66:81]
	v_mfma_f32_32x32x16_bf16 v[66:81], v[176:179], v[122:125], v[66:81]
	s_setprio 2
	ds_read_b128 v[162:165], v198 offset:20480
	ds_read_b128 v[166:169], v199 offset:20480
	ds_read_b128 v[170:173], v200 offset:20480
	ds_read_b128 v[176:179], v201 offset:20480
	s_waitcnt lgkmcnt(8)
	v_mfma_f32_32x32x16_bf16 v[182:197], v[130:133], v[118:121], 0
	v_mfma_f32_32x32x16_bf16 v[182:197], v[134:137], v[114:117], v[182:197]
	v_mfma_f32_32x32x16_bf16 v[182:197], v[138:141], v[110:113], v[182:197]
	v_mfma_f32_32x32x16_bf16 v[182:197], v[142:145], v[106:109], v[182:197]
	ds_read_b128 v[130:133], v198 offset:24576
	ds_read_b128 v[134:137], v198 offset:28672
	ds_read_b128 v[138:141], v198 offset:32768
	ds_read_b128 v[142:145], v198 offset:36864
	s_waitcnt lgkmcnt(8)
	v_mfma_f32_32x32x16_bf16 v[182:197], v[146:149], v[102:105], v[182:197]
	v_med3_f32 v66, v66, s4, v236
	v_exp_f32_e32 v66, v66
	v_med3_f32 v67, v67, s4, v236
	v_exp_f32_e32 v67, v67
	v_mfma_f32_32x32x16_bf16 v[182:197], v[150:153], v[98:101], v[182:197]
	v_med3_f32 v68, v68, s4, v236
	v_exp_f32_e32 v68, v68
	v_med3_f32 v69, v69, s4, v236
	v_exp_f32_e32 v69, v69
	v_mfma_f32_32x32x16_bf16 v[182:197], v[154:157], v[94:97], v[182:197]
	v_med3_f32 v70, v70, s4, v236
	v_exp_f32_e32 v70, v70
	v_med3_f32 v71, v71, s4, v236
	v_exp_f32_e32 v71, v71
	v_mfma_f32_32x32x16_bf16 v[182:197], v[158:161], v[90:93], v[182:197]
	v_med3_f32 v72, v72, s4, v236
	v_exp_f32_e32 v72, v72
	v_med3_f32 v73, v73, s4, v236
	v_exp_f32_e32 v73, v73
	ds_read_b128 v[146:149], v199 offset:24576
	ds_read_b128 v[150:153], v199 offset:28672
	ds_read_b128 v[154:157], v199 offset:32768
	ds_read_b128 v[158:161], v199 offset:36864
	s_waitcnt lgkmcnt(8)
	v_mfma_f32_32x32x16_bf16 v[182:197], v[162:165], v[86:89], v[182:197]
	v_med3_f32 v74, v74, s4, v236
	v_exp_f32_e32 v74, v74
	v_med3_f32 v75, v75, s4, v236
	v_exp_f32_e32 v75, v75
	v_add_f32_e32 v202, v66, v67
	v_add_f32_e32 v202, v202, v68
	v_mfma_f32_32x32x16_bf16 v[182:197], v[166:169], v[126:129], v[182:197]
	v_med3_f32 v76, v76, s4, v236
	v_exp_f32_e32 v76, v76
	v_med3_f32 v77, v77, s4, v236
	v_exp_f32_e32 v77, v77
	v_add_f32_e32 v202, v202, v69
	v_add_f32_e32 v202, v202, v70
	v_mfma_f32_32x32x16_bf16 v[182:197], v[170:173], v[82:85], v[182:197]
	v_med3_f32 v78, v78, s4, v236
	v_exp_f32_e32 v78, v78
	v_med3_f32 v79, v79, s4, v236
	v_exp_f32_e32 v79, v79
	v_add_f32_e32 v202, v202, v71
	v_add_f32_e32 v202, v202, v72
	v_mfma_f32_32x32x16_bf16 v[182:197], v[176:179], v[122:125], v[182:197]
	v_med3_f32 v80, v80, s4, v236
	v_exp_f32_e32 v80, v80
	v_med3_f32 v81, v81, s4, v236
	v_exp_f32_e32 v81, v81
	v_add_f32_e32 v202, v202, v73
	s_setprio 1
	ds_read_b128 v[162:165], v200 offset:24576
	ds_read_b128 v[166:169], v200 offset:28672
	ds_read_b128 v[170:173], v200 offset:32768
	ds_read_b128 v[176:179], v200 offset:36864
	v_cvt_pk_bf16_f32 v66, v66, v67
	v_cvt_pk_bf16_f32 v67, v68, v69
	v_cvt_pk_bf16_f32 v68, v70, v71
	v_cvt_pk_bf16_f32 v69, v72, v73
	v_add_f32_e32 v202, v202, v74
	v_add_f32_e32 v202, v202, v75
	s_waitcnt lgkmcnt(8)
	v_mfma_f32_32x32x16_bf16 v[50:65], v[66:69], v[130:133], v[50:65]
	v_med3_f32 v182, v182, s4, v236
	v_exp_f32_e32 v182, v182
	v_med3_f32 v183, v183, s4, v236
	v_exp_f32_e32 v183, v183
	v_add_f32_e32 v202, v202, v76
	v_add_f32_e32 v202, v202, v77
	v_mfma_f32_32x32x16_bf16 v[34:49], v[66:69], v[134:137], v[34:49]
	v_med3_f32 v184, v184, s4, v236
	v_exp_f32_e32 v184, v184
	v_med3_f32 v185, v185, s4, v236
	v_exp_f32_e32 v185, v185
	v_add_f32_e32 v202, v202, v78
	v_add_f32_e32 v202, v202, v79
	v_mfma_f32_32x32x16_bf16 v[18:33], v[66:69], v[138:141], v[18:33]
	v_med3_f32 v186, v186, s4, v236
	v_exp_f32_e32 v186, v186
	v_med3_f32 v187, v187, s4, v236
	v_exp_f32_e32 v187, v187
	v_add_f32_e32 v202, v202, v80
	v_add_f32_e32 v202, v202, v81
	v_mfma_f32_32x32x16_bf16 v[2:17], v[66:69], v[142:145], v[2:17]
	v_med3_f32 v188, v188, s4, v236
	v_exp_f32_e32 v188, v188
	v_med3_f32 v189, v189, s4, v236
	v_exp_f32_e32 v189, v189
	v_cvt_pk_bf16_f32 v70, v74, v75
	v_cvt_pk_bf16_f32 v71, v76, v77
	v_cvt_pk_bf16_f32 v72, v78, v79
	v_cvt_pk_bf16_f32 v73, v80, v81
	ds_read_b128 v[130:133], v201 offset:24576
	ds_read_b128 v[134:137], v201 offset:28672
	ds_read_b128 v[138:141], v201 offset:32768
	ds_read_b128 v[142:145], v201 offset:36864
	s_waitcnt lgkmcnt(8)
	v_mfma_f32_32x32x16_bf16 v[50:65], v[70:73], v[146:149], v[50:65]
	v_med3_f32 v190, v190, s4, v236
	v_exp_f32_e32 v190, v190
	v_med3_f32 v191, v191, s4, v236
	v_exp_f32_e32 v191, v191
	v_add_f32_e32 v203, v182, v183
	v_add_f32_e32 v203, v203, v184
	v_mfma_f32_32x32x16_bf16 v[34:49], v[70:73], v[150:153], v[34:49]
	v_med3_f32 v192, v192, s4, v236
	v_exp_f32_e32 v192, v192
	v_med3_f32 v193, v193, s4, v236
	v_exp_f32_e32 v193, v193
	v_add_f32_e32 v203, v203, v185
	v_add_f32_e32 v203, v203, v186
	v_mfma_f32_32x32x16_bf16 v[18:33], v[70:73], v[154:157], v[18:33]
	v_med3_f32 v194, v194, s4, v236
	v_exp_f32_e32 v194, v194
	v_med3_f32 v195, v195, s4, v236
	v_exp_f32_e32 v195, v195
	v_add_f32_e32 v203, v203, v187
	v_mfma_f32_32x32x16_bf16 v[2:17], v[70:73], v[158:161], v[2:17]
	v_med3_f32 v196, v196, s4, v236
	v_exp_f32_e32 v196, v196
	v_med3_f32 v197, v197, s4, v236
	v_exp_f32_e32 v197, v197
	v_add_f32_e32 v203, v203, v188
	v_cvt_pk_bf16_f32 v182, v182, v183
	v_cvt_pk_bf16_f32 v183, v184, v185
	v_cvt_pk_bf16_f32 v184, v186, v187
	v_cvt_pk_bf16_f32 v185, v188, v189
	v_add_f32_e32 v203, v203, v189
	s_setprio 0
	s_waitcnt lgkmcnt(4)
	v_mfma_f32_32x32x16_bf16 v[50:65], v[182:185], v[162:165], v[50:65]
	v_add_f32_e32 v203, v203, v190
	v_add_f32_e32 v203, v203, v191
	v_add_f32_e32 v203, v203, v192
	v_mfma_f32_32x32x16_bf16 v[34:49], v[182:185], v[166:169], v[34:49]
	v_add_f32_e32 v203, v203, v193
	v_add_f32_e32 v203, v203, v194
	v_add_f32_e32 v203, v203, v195
	v_mfma_f32_32x32x16_bf16 v[18:33], v[182:185], v[170:173], v[18:33]
	v_add_f32_e32 v203, v203, v196
	v_add_f32_e32 v203, v203, v197
	v_cvt_pk_bf16_f32 v186, v190, v191
	v_cvt_pk_bf16_f32 v187, v192, v193
	v_cvt_pk_bf16_f32 v188, v194, v195
	v_cvt_pk_bf16_f32 v189, v196, v197
	v_mfma_f32_32x32x16_bf16 v[2:17], v[182:185], v[176:179], v[2:17]
	v_add_f32_e32 v202, v202, v203
	v_add_f32_e32 v0, v0, v202
	s_waitcnt lgkmcnt(0)
	v_mfma_f32_32x32x16_bf16 v[50:65], v[186:189], v[130:133], v[50:65]
	v_mfma_f32_32x32x16_bf16 v[34:49], v[186:189], v[134:137], v[34:49]
	v_mfma_f32_32x32x16_bf16 v[18:33], v[186:189], v[138:141], v[18:33]
	v_mfma_f32_32x32x16_bf16 v[2:17], v[186:189], v[142:145], v[2:17]
	s_waitcnt vmcnt(0) lgkmcnt(0)
	s_branch .LBB0_573
